# GEMM loop: remaining m0-to-DMA wait states filled with the loop-carried scalar pointer updates (3 more nops removed)
# speedup vs baseline: 1.0048x; 1.0037x over previous
; #define PG8_STAGE(bufoff, gbase, voff) do { _Pragma("unroll") for (int _i = 0; _i < 2; ++_i) \
;         __builtin_amdgcn_global_load_lds((const unsigned*)((const char*)(gbase) + (voff)[_i]), (LAS unsigned*)(lds + (bufoff) + ldsw + _i * 8192), 16, 0, 0); } while (0)
; #define PG8_LDA(dst, b, h) do { _Pragma("unroll") for (int m = 0; m < 4; ++m) _Pragma("unroll") for (int k = 0; k < 2; ++k) dst[m][k] = *(const LAS h16x8*)(lds + PG8_SA(b, h) + aoff + m * 2048 + k * 1024); } while (0)
; #define PG8_LDB(dst, b, h) do { _Pragma("unroll") for (int n = 0; n < 2; ++n) _Pragma("unroll") for (int k = 0; k < 2; ++k) dst[n][k] = *(const LAS h16x8*)(lds + PG8_SB(b, h) + boff + n * 2048 + k * 1024); } while (0)
; #define PG8_MMA(ai, bj, At, Bt) do { __builtin_amdgcn_s_setprio(1); _Pragma("unroll") for (int m = 0; m < 4; ++m) _Pragma("unroll") for (int n = 0; n < 2; ++n) _Pragma("unroll") for (int k = 0; k < 2; ++k) \
;         acc[ai][bj][m][n] = __builtin_amdgcn_mfma_f32_16x16x32_f16(Bt[n][k], At[m][k], acc[ai][bj][m][n], 0, 0, 0); __builtin_amdgcn_s_setprio(0); } while (0)
; #define PG8_WAIT_L(n) asm volatile("s_waitcnt lgkmcnt(" #n ")" ::: "memory")
; #define PG8_BAR __builtin_amdgcn_s_barrier()
; #define PG8_SCHED __builtin_amdgcn_sched_barrier(0)
; __device__ __forceinline__ void gemm_phase(LAS unsigned char* lds, const Gemm g, const StaticOrder& S, const Epi& E) {
;     ...
;             const bool last = (t == nt - 2);
;             const char* a1 = cA + PG8_KOFF(t + 1);
;             const char* a2 = last ? nA : cA + PG8_KOFF(t + 2); const char* b2 = last ? nB : cB + (size_t)(t + 2) * kstep;
;             const char* a3 = a2 + kstep; const char* b3 = b2 + kstep;
;             PG8_LDB(B0, 0, 0); PG8_SCHED; PG8_LDA(At, 0, 0); PG8_STAGE(PG8_SA(1, 1), a1 + hstepA, voffA);
;             PG8_WAIT_L(8); PG8_BAR; PG8_WAIT_L(0); PG8_MMA(0, 0, At, B0); PG8_BAR; PG8_SCHED;
;             PG8_LDB(B1, 0, 1); PG8_STAGE(PG8_SB(0, 0), b2, voffB);
;             PG8_BAR; PG8_WAIT_L(0); PG8_MMA(0, 1, At, B1); PG8_BAR;
;             PG8_LDA(At, 0, 1); PG8_STAGE(PG8_SA(0, 0), a2, voffA);
;             PG8_BAR; PG8_WAIT_L(0); PG8_MMA(1, 0, At, B0); PG8_BAR; PG8_SCHED;
.Lprio_skip:
.LBB0_762:
	s_cmp_gt_u32 s34, 15
	s_cselect_b64 s[36:37], -1, 0
	s_and_b64 s[36:37], s[6:7], s[36:37]
	s_and_b64 s[36:37], s[36:37], exec
	s_cselect_b32 s42, 0xfffff000, 0
	s_cselect_b32 s43, -1, 0
	s_add_i32 s38, s34, 2
	s_cmp_gt_u32 s34, 13
	s_cselect_b64 s[36:37], -1, 0
	s_and_b64 s[36:37], s[6:7], s[36:37]
	s_and_b64 s[36:37], s[36:37], exec
	s_cselect_b32 s36, 0xfffff000, 0
	s_cselect_b32 s35, -1, 0
	s_add_u32 s36, s0, s36
	s_addc_u32 s35, s1, s35
	s_add_u32 s36, s36, 0x80
	s_addc_u32 s35, s35, 0
	ds_read_b128 v[128:131], v224
	ds_read_b128 v[132:135], v224 offset:1024
	ds_read_b128 v[136:139], v224 offset:2048
	ds_read_b128 v[140:143], v224 offset:3072
	s_cmp_eq_u32 s66, s34
	s_cselect_b32 s34, s4, s36
	s_cselect_b32 s35, s5, s35
	s_cselect_b32 s37, s29, s33
	s_cselect_b32 s36, s28, s27
	s_add_u32 s86, s0, s42
	s_addc_u32 s87, s1, s43
	s_add_i32 m0, s58, 0xc000
	ds_read_b128 v[144:147], v239
	ds_read_b128 v[148:151], v239 offset:1024
	ds_read_b128 v[152:155], v239 offset:2048
	ds_read_b128 v[156:159], v239 offset:3072
	ds_read_b128 v[160:163], v239 offset:4096
	ds_read_b128 v[164:167], v239 offset:5120
	ds_read_b128 v[168:171], v239 offset:6144
	global_load_lds_dwordx4 v212, s[86:87]
	s_add_i32 m0, s58, 0xe000
	ds_read_b128 v[172:175], v239 offset:7168
	global_load_lds_dwordx4 v214, s[86:87]
	s_waitcnt lgkmcnt(8)
	s_barrier
	s_waitcnt lgkmcnt(0)
	v_mfma_f32_16x16x32_f16 v[124:127], v[128:131], v[144:147], v[124:127]
	v_mfma_f32_16x16x32_f16 v[120:123], v[136:139], v[144:147], v[120:123]
	v_mfma_f32_16x16x32_f16 v[108:111], v[128:131], v[152:155], v[108:111]
	v_mfma_f32_16x16x32_f16 v[104:107], v[136:139], v[152:155], v[104:107]
	v_mfma_f32_16x16x32_f16 v[92:95], v[128:131], v[160:163], v[92:95]
	v_mfma_f32_16x16x32_f16 v[88:91], v[136:139], v[160:163], v[88:91]
	v_mfma_f32_16x16x32_f16 v[76:79], v[128:131], v[168:171], v[76:79]
	v_mfma_f32_16x16x32_f16 v[72:75], v[136:139], v[168:171], v[72:75]
	v_mfma_f32_16x16x32_f16 v[124:127], v[132:135], v[148:151], v[124:127]
	v_mfma_f32_16x16x32_f16 v[120:123], v[140:143], v[148:151], v[120:123]
	v_mfma_f32_16x16x32_f16 v[108:111], v[132:135], v[156:159], v[108:111]
	v_mfma_f32_16x16x32_f16 v[104:107], v[140:143], v[156:159], v[104:107]
	v_mfma_f32_16x16x32_f16 v[92:95], v[132:135], v[164:167], v[92:95]
	v_mfma_f32_16x16x32_f16 v[88:91], v[140:143], v[164:167], v[88:91]
	v_mfma_f32_16x16x32_f16 v[76:79], v[132:135], v[172:175], v[76:79]
	v_mfma_f32_16x16x32_f16 v[72:75], v[140:143], v[172:175], v[72:75]
	s_barrier
	s_add_u32 s86, s36, 0x80
	s_addc_u32 s87, s37, 0
	s_add_i32 m0, s31, 0x10000
	ds_read_b128 v[176:179], v225
	ds_read_b128 v[180:183], v225 offset:1024
	ds_read_b128 v[184:187], v225 offset:2048
	global_load_lds_dwordx4 v206, s[36:37]
	s_add_i32 m0, s31, 0x12000
	ds_read_b128 v[188:191], v225 offset:3072
	global_load_lds_dwordx4 v210, s[36:37]
	s_barrier
	s_waitcnt lgkmcnt(0)
	v_mfma_f32_16x16x32_f16 v[116:119], v[176:179], v[144:147], v[116:119]
	v_mfma_f32_16x16x32_f16 v[112:115], v[184:187], v[144:147], v[112:115]
	v_mfma_f32_16x16x32_f16 v[100:103], v[176:179], v[152:155], v[100:103]
	v_mfma_f32_16x16x32_f16 v[96:99], v[184:187], v[152:155], v[96:99]
	v_mfma_f32_16x16x32_f16 v[84:87], v[176:179], v[160:163], v[84:87]
	v_mfma_f32_16x16x32_f16 v[80:83], v[184:187], v[160:163], v[80:83]
	v_mfma_f32_16x16x32_f16 v[68:71], v[176:179], v[168:171], v[68:71]
	v_mfma_f32_16x16x32_f16 v[64:67], v[184:187], v[168:171], v[64:67]
	v_mfma_f32_16x16x32_f16 v[116:119], v[180:183], v[148:151], v[116:119]
	v_mfma_f32_16x16x32_f16 v[112:115], v[188:191], v[148:151], v[112:115]
	v_mfma_f32_16x16x32_f16 v[100:103], v[180:183], v[156:159], v[100:103]
	v_mfma_f32_16x16x32_f16 v[96:99], v[188:191], v[156:159], v[96:99]
	v_mfma_f32_16x16x32_f16 v[84:87], v[180:183], v[164:167], v[84:87]
	v_mfma_f32_16x16x32_f16 v[80:83], v[188:191], v[164:167], v[80:83]
	v_mfma_f32_16x16x32_f16 v[68:71], v[180:183], v[172:175], v[68:71]
	v_mfma_f32_16x16x32_f16 v[64:67], v[188:191], v[172:175], v[64:67]
	s_mov_b32 m0, s58
	s_add_u32 s88, s34, 0x80
	s_addc_u32 s89, s35, 0
	s_barrier
	ds_read_b128 v[144:147], v239 offset:16384
	ds_read_b128 v[148:151], v239 offset:17408
	ds_read_b128 v[152:155], v239 offset:18432
	ds_read_b128 v[156:159], v239 offset:19456
	ds_read_b128 v[160:163], v239 offset:20480
	ds_read_b128 v[164:167], v239 offset:21504
	ds_read_b128 v[168:171], v239 offset:22528
	global_load_lds_dwordx4 v204, s[34:35]
	s_mov_b32 m0, s59
	ds_read_b128 v[172:175], v239 offset:23552
	global_load_lds_dwordx4 v208, s[34:35]
	s_barrier
	s_waitcnt lgkmcnt(0)
	v_mfma_f32_16x16x32_f16 v[60:63], v[128:131], v[144:147], v[60:63]
	v_mfma_f32_16x16x32_f16 v[56:59], v[136:139], v[144:147], v[56:59]
	v_mfma_f32_16x16x32_f16 v[44:47], v[128:131], v[152:155], v[44:47]
	v_mfma_f32_16x16x32_f16 v[40:43], v[136:139], v[152:155], v[40:43]
	v_mfma_f32_16x16x32_f16 v[28:31], v[128:131], v[160:163], v[28:31]
	v_mfma_f32_16x16x32_f16 v[24:27], v[136:139], v[160:163], v[24:27]
	v_mfma_f32_16x16x32_f16 v[12:15], v[128:131], v[168:171], v[12:15]
	v_mfma_f32_16x16x32_f16 v[8:11], v[136:139], v[168:171], v[8:11]
	v_mfma_f32_16x16x32_f16 v[60:63], v[132:135], v[148:151], v[60:63]
	v_mfma_f32_16x16x32_f16 v[56:59], v[140:143], v[148:151], v[56:59]
	v_mfma_f32_16x16x32_f16 v[44:47], v[132:135], v[156:159], v[44:47]
	v_mfma_f32_16x16x32_f16 v[40:43], v[140:143], v[156:159], v[40:43]
	v_mfma_f32_16x16x32_f16 v[28:31], v[132:135], v[164:167], v[28:31]
	v_mfma_f32_16x16x32_f16 v[24:27], v[140:143], v[164:167], v[24:27]
	v_mfma_f32_16x16x32_f16 v[12:15], v[132:135], v[172:175], v[12:15]
	v_mfma_f32_16x16x32_f16 v[8:11], v[140:143], v[172:175], v[8:11]
	s_barrier
; #define PG8_STAGE(bufoff, gbase, voff) do { _Pragma("unroll") for (int _i = 0; _i < 2; ++_i) \
;         __builtin_amdgcn_global_load_lds((const unsigned*)((const char*)(gbase) + (voff)[_i]), (LAS unsigned*)(lds + (bufoff) + ldsw + _i * 8192), 16, 0, 0); } while (0)
; #define PG8_MMA(ai, bj, At, Bt) do { __builtin_amdgcn_s_setprio(1); _Pragma("unroll") for (int m = 0; m < 4; ++m) _Pragma("unroll") for (int n = 0; n < 2; ++n) _Pragma("unroll") for (int k = 0; k < 2; ++k) \
;         acc[ai][bj][m][n] = __builtin_amdgcn_mfma_f32_16x16x32_f16(Bt[n][k], At[m][k], acc[ai][bj][m][n], 0, 0, 0); __builtin_amdgcn_s_setprio(0); } while (0)
; #define PG8_WAIT_V(n) asm volatile("s_waitcnt vmcnt(" #n ")" ::: "memory")
; #define PG8_BAR __builtin_amdgcn_s_barrier()
; __device__ __forceinline__ void gemm_phase(LAS unsigned char* lds, const Gemm g, const StaticOrder& S, const Epi& E) {
;     ...
;             PG8_STAGE(PG8_SB(0, 1), b2 + hstepB, voffB);
;             PG8_WAIT_V(6); PG8_BAR; PG8_MMA(1, 1, At, B1); PG8_BAR;
	s_add_u32 s36, s36, s18
	s_addc_u32 s37, s37, s19
	s_add_i32 m0, s31, 0x14000
	s_add_u32 s96, s36, 0x80
	s_addc_u32 s97, s37, 0
	global_load_lds_dwordx4 v206, s[36:37]
	s_add_i32 m0, s31, 0x16000
	s_nop 0
	global_load_lds_dwordx4 v210, s[36:37]
	s_waitcnt vmcnt(6)
	s_barrier
	v_mfma_f32_16x16x32_f16 v[52:55], v[176:179], v[144:147], v[52:55]
	v_mfma_f32_16x16x32_f16 v[48:51], v[184:187], v[144:147], v[48:51]
	v_mfma_f32_16x16x32_f16 v[36:39], v[176:179], v[152:155], v[36:39]
	v_mfma_f32_16x16x32_f16 v[32:35], v[184:187], v[152:155], v[32:35]
	v_mfma_f32_16x16x32_f16 v[20:23], v[176:179], v[160:163], v[20:23]
	v_mfma_f32_16x16x32_f16 v[16:19], v[184:187], v[160:163], v[16:19]
	v_mfma_f32_16x16x32_f16 v[4:7], v[176:179], v[168:171], v[4:7]
	v_mfma_f32_16x16x32_f16 v[0:3], v[184:187], v[168:171], v[0:3]
	v_mfma_f32_16x16x32_f16 v[52:55], v[180:183], v[148:151], v[52:55]
	v_mfma_f32_16x16x32_f16 v[48:51], v[188:191], v[148:151], v[48:51]
	v_mfma_f32_16x16x32_f16 v[36:39], v[180:183], v[156:159], v[36:39]
	v_mfma_f32_16x16x32_f16 v[32:35], v[188:191], v[156:159], v[32:35]
	v_mfma_f32_16x16x32_f16 v[20:23], v[180:183], v[164:167], v[20:23]
	v_mfma_f32_16x16x32_f16 v[16:19], v[188:191], v[164:167], v[16:19]
	v_mfma_f32_16x16x32_f16 v[4:7], v[180:183], v[172:175], v[4:7]
	v_mfma_f32_16x16x32_f16 v[0:3], v[188:191], v[172:175], v[0:3]
	s_barrier
	ds_read_b128 v[128:131], v241
	ds_read_b128 v[132:135], v241 offset:1024
	ds_read_b128 v[136:139], v241 offset:2048
	ds_read_b128 v[140:143], v241 offset:3072
	s_add_u32 s34, s34, s16
	s_addc_u32 s35, s35, s17
	s_mov_b32 m0, s60
	ds_read_b128 v[144:147], v239 offset:32768
	ds_read_b128 v[148:151], v239 offset:33792
	ds_read_b128 v[152:155], v239 offset:34816
	ds_read_b128 v[156:159], v239 offset:35840
	ds_read_b128 v[160:163], v239 offset:36864
	ds_read_b128 v[164:167], v239 offset:37888
	ds_read_b128 v[168:171], v239 offset:38912
	global_load_lds_dwordx4 v204, s[34:35]
	s_mov_b32 m0, s61
	ds_read_b128 v[172:175], v239 offset:39936
	global_load_lds_dwordx4 v208, s[34:35]
	s_waitcnt lgkmcnt(8)
	s_barrier
	s_waitcnt lgkmcnt(0)
	v_mfma_f32_16x16x32_f16 v[124:127], v[128:131], v[144:147], v[124:127]
	v_mfma_f32_16x16x32_f16 v[120:123], v[136:139], v[144:147], v[120:123]
	v_mfma_f32_16x16x32_f16 v[108:111], v[128:131], v[152:155], v[108:111]
	v_mfma_f32_16x16x32_f16 v[104:107], v[136:139], v[152:155], v[104:107]
	v_mfma_f32_16x16x32_f16 v[92:95], v[128:131], v[160:163], v[92:95]
	v_mfma_f32_16x16x32_f16 v[88:91], v[136:139], v[160:163], v[88:91]
	v_mfma_f32_16x16x32_f16 v[76:79], v[128:131], v[168:171], v[76:79]
	v_mfma_f32_16x16x32_f16 v[72:75], v[136:139], v[168:171], v[72:75]
	v_mfma_f32_16x16x32_f16 v[124:127], v[132:135], v[148:151], v[124:127]
	v_mfma_f32_16x16x32_f16 v[120:123], v[140:143], v[148:151], v[120:123]
	v_mfma_f32_16x16x32_f16 v[108:111], v[132:135], v[156:159], v[108:111]
	v_mfma_f32_16x16x32_f16 v[104:107], v[140:143], v[156:159], v[104:107]
	v_mfma_f32_16x16x32_f16 v[92:95], v[132:135], v[164:167], v[92:95]
	v_mfma_f32_16x16x32_f16 v[88:91], v[140:143], v[164:167], v[88:91]
	v_mfma_f32_16x16x32_f16 v[76:79], v[132:135], v[172:175], v[76:79]
	v_mfma_f32_16x16x32_f16 v[72:75], v[140:143], v[172:175], v[72:75]
	s_barrier
	s_add_i32 m0, s31, 0x18000
	ds_read_b128 v[176:179], v248
	ds_read_b128 v[180:183], v248 offset:1024
	ds_read_b128 v[184:187], v248 offset:2048
	global_load_lds_dwordx4 v206, s[86:87]
	s_add_i32 m0, s31, 0x1a000
	ds_read_b128 v[188:191], v248 offset:3072
	global_load_lds_dwordx4 v210, s[86:87]
	s_barrier
; #define PG8_STAGE(bufoff, gbase, voff) do { _Pragma("unroll") for (int _i = 0; _i < 2; ++_i) \
;         __builtin_amdgcn_global_load_lds((const unsigned*)((const char*)(gbase) + (voff)[_i]), (LAS unsigned*)(lds + (bufoff) + ldsw + _i * 8192), 16, 0, 0); } while (0)
; #define PG8_MMA(ai, bj, At, Bt) do { __builtin_amdgcn_s_setprio(1); _Pragma("unroll") for (int m = 0; m < 4; ++m) _Pragma("unroll") for (int n = 0; n < 2; ++n) _Pragma("unroll") for (int k = 0; k < 2; ++k) \
;         acc[ai][bj][m][n] = __builtin_amdgcn_mfma_f32_16x16x32_f16(Bt[n][k], At[m][k], acc[ai][bj][m][n], 0, 0, 0); __builtin_amdgcn_s_setprio(0); } while (0)
; #define PG8_WAIT_V(n) asm volatile("s_waitcnt vmcnt(" #n ")" ::: "memory")
; #define PG8_BAR __builtin_amdgcn_s_barrier()
; __device__ __forceinline__ void gemm_phase(LAS unsigned char* lds, const Gemm g, const StaticOrder& S, const Epi& E) {
;     ...
;             PG8_STAGE(PG8_SB(1, 1), b3 + hstepB, voffB);
;             PG8_WAIT_V(6); PG8_BAR; PG8_MMA(1, 1, At, B1); PG8_BAR;
;         }
;         E(acc, cur, wr, wc, fr, fq);
	s_waitcnt lgkmcnt(0)
	v_mfma_f32_16x16x32_f16 v[116:119], v[176:179], v[144:147], v[116:119]
	v_mfma_f32_16x16x32_f16 v[112:115], v[184:187], v[144:147], v[112:115]
	v_mfma_f32_16x16x32_f16 v[100:103], v[176:179], v[152:155], v[100:103]
	v_mfma_f32_16x16x32_f16 v[96:99], v[184:187], v[152:155], v[96:99]
	v_mfma_f32_16x16x32_f16 v[84:87], v[176:179], v[160:163], v[84:87]
	v_mfma_f32_16x16x32_f16 v[80:83], v[184:187], v[160:163], v[80:83]
	v_mfma_f32_16x16x32_f16 v[68:71], v[176:179], v[168:171], v[68:71]
	v_mfma_f32_16x16x32_f16 v[64:67], v[184:187], v[168:171], v[64:67]
	v_mfma_f32_16x16x32_f16 v[116:119], v[180:183], v[148:151], v[116:119]
	v_mfma_f32_16x16x32_f16 v[112:115], v[188:191], v[148:151], v[112:115]
	v_mfma_f32_16x16x32_f16 v[100:103], v[180:183], v[156:159], v[100:103]
	v_mfma_f32_16x16x32_f16 v[96:99], v[188:191], v[156:159], v[96:99]
	v_mfma_f32_16x16x32_f16 v[84:87], v[180:183], v[164:167], v[84:87]
	v_mfma_f32_16x16x32_f16 v[80:83], v[188:191], v[164:167], v[80:83]
	v_mfma_f32_16x16x32_f16 v[68:71], v[180:183], v[172:175], v[68:71]
	v_mfma_f32_16x16x32_f16 v[64:67], v[188:191], v[172:175], v[64:67]
	s_mov_b32 m0, s62
	s_barrier
	ds_read_b128 v[144:147], v239 offset:49152
	ds_read_b128 v[148:151], v239 offset:50176
	ds_read_b128 v[152:155], v239 offset:51200
	ds_read_b128 v[156:159], v239 offset:52224
	ds_read_b128 v[160:163], v239 offset:53248
	ds_read_b128 v[164:167], v239 offset:54272
	ds_read_b128 v[168:171], v239 offset:55296
	global_load_lds_dwordx4 v204, s[88:89]
	s_mov_b32 m0, s63
	ds_read_b128 v[172:175], v239 offset:56320
	global_load_lds_dwordx4 v208, s[88:89]
	s_barrier
	s_waitcnt lgkmcnt(0)
	v_mfma_f32_16x16x32_f16 v[60:63], v[128:131], v[144:147], v[60:63]
	v_mfma_f32_16x16x32_f16 v[56:59], v[136:139], v[144:147], v[56:59]
	v_mfma_f32_16x16x32_f16 v[44:47], v[128:131], v[152:155], v[44:47]
	v_mfma_f32_16x16x32_f16 v[40:43], v[136:139], v[152:155], v[40:43]
	v_mfma_f32_16x16x32_f16 v[28:31], v[128:131], v[160:163], v[28:31]
	v_mfma_f32_16x16x32_f16 v[24:27], v[136:139], v[160:163], v[24:27]
	v_mfma_f32_16x16x32_f16 v[12:15], v[128:131], v[168:171], v[12:15]
	v_mfma_f32_16x16x32_f16 v[8:11], v[136:139], v[168:171], v[8:11]
	v_mfma_f32_16x16x32_f16 v[60:63], v[132:135], v[148:151], v[60:63]
	v_mfma_f32_16x16x32_f16 v[56:59], v[140:143], v[148:151], v[56:59]
	v_mfma_f32_16x16x32_f16 v[44:47], v[132:135], v[156:159], v[44:47]
	v_mfma_f32_16x16x32_f16 v[40:43], v[140:143], v[156:159], v[40:43]
	v_mfma_f32_16x16x32_f16 v[28:31], v[132:135], v[164:167], v[28:31]
	v_mfma_f32_16x16x32_f16 v[24:27], v[140:143], v[164:167], v[24:27]
	v_mfma_f32_16x16x32_f16 v[12:15], v[132:135], v[172:175], v[12:15]
	v_mfma_f32_16x16x32_f16 v[8:11], v[140:143], v[172:175], v[8:11]
	s_barrier
	s_add_i32 m0, s31, 0x1c000
	s_add_u32 s0, s0, 0x100
	s_addc_u32 s1, s1, 0
	global_load_lds_dwordx4 v206, s[96:97]
	s_add_i32 m0, s31, 0x1e000
	s_add_u32 s27, s27, 0x100
	s_addc_u32 s33, s33, 0
	global_load_lds_dwordx4 v210, s[96:97]
	s_waitcnt vmcnt(6)
	s_barrier
	v_mfma_f32_16x16x32_f16 v[52:55], v[176:179], v[144:147], v[52:55]
	v_mfma_f32_16x16x32_f16 v[48:51], v[184:187], v[144:147], v[48:51]
	v_mfma_f32_16x16x32_f16 v[36:39], v[176:179], v[152:155], v[36:39]
	v_mfma_f32_16x16x32_f16 v[32:35], v[184:187], v[152:155], v[32:35]
	v_mfma_f32_16x16x32_f16 v[20:23], v[176:179], v[160:163], v[20:23]
	v_mfma_f32_16x16x32_f16 v[16:19], v[184:187], v[160:163], v[16:19]
	v_mfma_f32_16x16x32_f16 v[4:7], v[176:179], v[168:171], v[4:7]
	v_mfma_f32_16x16x32_f16 v[0:3], v[184:187], v[168:171], v[0:3]
	v_mfma_f32_16x16x32_f16 v[52:55], v[180:183], v[148:151], v[52:55]
	v_mfma_f32_16x16x32_f16 v[48:51], v[188:191], v[148:151], v[48:51]
	v_mfma_f32_16x16x32_f16 v[36:39], v[180:183], v[156:159], v[36:39]
	v_mfma_f32_16x16x32_f16 v[32:35], v[188:191], v[156:159], v[32:35]
	v_mfma_f32_16x16x32_f16 v[20:23], v[180:183], v[164:167], v[20:23]
	v_mfma_f32_16x16x32_f16 v[16:19], v[188:191], v[164:167], v[16:19]
	v_mfma_f32_16x16x32_f16 v[4:7], v[180:183], v[172:175], v[4:7]
	v_mfma_f32_16x16x32_f16 v[0:3], v[188:191], v[172:175], v[0:3]
	s_cmp_ge_u32 s38, s64
	s_mov_b32 s34, s38
	s_barrier
	s_cbranch_scc0 .LBB0_762
	s_setprio 0
	s_lshl_b32 s0, s84, 8
	s_or_b32 s27, s0, s65
	v_lshl_add_u32 v240, s30, 8, v200
	v_or_b32_e32 v216, s27, v202
	s_cmp_eq_u32 s93, 3
	s_cbranch_scc1 .Lst16_fast
	s_cmp_eq_u32 s93, 1
	s_cbranch_scc0 .Llora_no
	s_lshr_b32 s0, s84, 2
	s_cmp_lt_u32 s0, 2
	s_cbranch_scc1 .Llora_fast
